# G1B sigmoid rcp+Newton, accumulator zeroing hoisted into prologue load shadow, p2 silu division chains via rcp+Newton
# baseline (speedup 1.0000x reference)
; DEVI float bfs(short h) { return __uint_as_float(((unsigned)(u16)h) << 16); }
; __device__ void phase_p2(const P& p, int l) {
;     ...
;       u16 ob = f2bf(o);
;       u16* kh = (u16*)(ws + O_KH) + ((size_t)(b * 4) * TPB + t) * 192 + 128 + lane;
; #pragma unroll
;       for (int h = 0; h < 4; ++h) kh[(size_t)h * TPB * 192] = ob;
;     }
;     {
;       float s[8] = {0, 0, 0, 0, 0, 0, 0, 0};
; #pragma unroll
;       for (int k = 0; k < 16; ++k)
; #pragma unroll
;         for (int i = 0; i < 8; ++i) s[i] += bfs(wv[k][i]);
;       float ic = 1.f / (float)(hi - lo + 1);
; #pragma unroll
;       for (int i = 0; i < 8; ++i) s[i] = s[i] * ic - bfs(wv[8][i]);
.LBB0_141:
	s_or_b64 exec, exec, s[2:3]
	v_bfe_u32 v127, v126, 16, 1
	v_add3_u32 v126, v126, v127, s33
	v_lshrrev_b32_e32 v130, 16, v126
	v_lshlrev_b32_e32 v126, 2, v191
	v_mul_hi_i32_i24_e32 v127, 0x1100, v126
	v_mul_i32_i24_e32 v126, 0x1100, v126
	v_ashrrev_i32_e32 v191, 31, v190
	v_lshl_add_u64 v[126:127], v[126:127], 0, v[190:191]
	s_waitcnt lgkmcnt(0)
	v_mov_b64_e32 v[128:129], s[36:37]
	s_movk_i32 s2, 0x180
	v_mad_u64_u32 v[128:129], s[0:1], v126, s2, v[128:129]
	v_mov_b32_e32 v126, v129
	v_mad_u64_u32 v[126:127], s[0:1], v127, s2, v[126:127]
	v_mov_b32_e32 v129, v126
	v_lshl_add_u64 v[126:127], v[128:129], 0, v[0:1]
	s_mov_b32 s0, 0x1b28a000
	v_add_co_u32_e32 v128, vcc, s0, v126
	s_waitcnt vmcnt(0)
	v_and_b32_e32 v191, 0xffff0000, v90
	v_lshlrev_b32_e32 v190, 16, v90
	v_sub_u32_e32 v90, v215, v214
	v_addc_co_u32_e32 v129, vcc, 0, v127, vcc
	s_mov_b32 s0, 0x1b422000
	v_add_u32_e32 v90, 1, v90
	global_store_short v[128:129], v130, off offset:256
	v_add_co_u32_e32 v128, vcc, s0, v126
	v_cvt_f32_i32_e32 v90, v90
	s_nop 0
	v_addc_co_u32_e32 v129, vcc, 0, v127, vcc
	s_mov_b32 s0, 0x1b5ba000
	global_store_short v[128:129], v130, off offset:256
	v_add_co_u32_e32 v128, vcc, s0, v126
	s_mov_b32 s0, 0x1b752000
	s_nop 0
	v_addc_co_u32_e32 v129, vcc, 0, v127, vcc
	v_add_co_u32_e32 v126, vcc, s0, v126
	v_and_b32_e32 v193, 0xffff0000, v91
	v_lshlrev_b32_e32 v192, 16, v91
	v_div_scale_f32 v91, s[0:1], v90, v90, 1.0
	v_and_b32_e32 v219, 0xffff0000, v106
	v_lshlrev_b32_e32 v218, 16, v106
	v_rcp_f32_e32 v106, v91
	v_addc_co_u32_e32 v127, vcc, 0, v127, vcc
	global_store_short v[126:127], v130, off offset:256
	v_and_b32_e32 v127, 0xffff0000, v94
	v_lshlrev_b32_e32 v126, 16, v94
	global_store_short v[128:129], v130, off offset:256
	v_pk_add_f32 v[128:129], v[126:127], 0 op_sel_hi:[1,0]
	v_and_b32_e32 v221, 0xffff0000, v107
	v_lshlrev_b32_e32 v220, 16, v107
	v_fma_f32 v107, -v91, v106, 1.0
	v_pk_add_f32 v[128:129], v[128:129], v[190:191]
	v_and_b32_e32 v127, 0xffff0000, v95
	v_lshlrev_b32_e32 v126, 16, v95
	v_fmac_f32_e32 v106, v107, v106
	v_div_scale_f32 v107, vcc, 1.0, v90, 1.0
	v_pk_add_f32 v[128:129], v[128:129], v[218:219]
	v_and_b32_e32 v191, 0xffff0000, v66
	v_lshlrev_b32_e32 v190, 16, v66
	v_pk_add_f32 v[130:131], v[126:127], 0 op_sel_hi:[1,0]
	v_and_b32_e32 v95, 0xffff0000, v96
	v_lshlrev_b32_e32 v94, 16, v96
	v_and_b32_e32 v217, 0xffff0000, v92
	v_lshlrev_b32_e32 v216, 16, v92
	v_and_b32_e32 v127, 0xffff0000, v93
	v_lshlrev_b32_e32 v126, 16, v93
	v_and_b32_e32 v223, 0xffff0000, v108
	v_lshlrev_b32_e32 v222, 16, v108
	v_and_b32_e32 v225, 0xffff0000, v109
	v_lshlrev_b32_e32 v224, 16, v109
	v_and_b32_e32 v109, 0xffff0000, v166
	v_lshlrev_b32_e32 v108, 16, v166
	v_and_b32_e32 v227, 0xffff0000, v167
	v_lshlrev_b32_e32 v226, 16, v167
	v_and_b32_e32 v167, 0xffff0000, v168
	v_lshlrev_b32_e32 v166, 16, v168
	v_and_b32_e32 v93, 0xffff0000, v169
	v_lshlrev_b32_e32 v92, 16, v169
	v_and_b32_e32 v169, 0xffff0000, v162
	v_lshlrev_b32_e32 v168, 16, v162
	v_and_b32_e32 v229, 0xffff0000, v163
	v_lshlrev_b32_e32 v228, 16, v163
	v_and_b32_e32 v163, 0xffff0000, v164
	v_lshlrev_b32_e32 v162, 16, v164
	v_mul_f32_e32 v164, v107, v106
	v_pk_add_f32 v[128:129], v[128:129], v[190:191]
	v_and_b32_e32 v191, 0xffff0000, v74
	v_lshlrev_b32_e32 v190, 16, v74
	v_pk_add_f32 v[132:133], v[94:95], 0 op_sel_hi:[1,0]
	v_and_b32_e32 v95, 0xffff0000, v97
	v_lshlrev_b32_e32 v94, 16, v97
	v_and_b32_e32 v97, 0xffff0000, v165
	v_lshlrev_b32_e32 v96, 16, v165
	v_fma_f32 v165, -v91, v164, v107
	v_pk_add_f32 v[128:129], v[128:129], v[190:191]
	v_and_b32_e32 v191, 0xffff0000, v70
	v_lshlrev_b32_e32 v190, 16, v70
	v_fmac_f32_e32 v164, v165, v106
	v_pk_add_f32 v[128:129], v[128:129], v[190:191]
	v_and_b32_e32 v191, 0xffff0000, v82
	v_lshlrev_b32_e32 v190, 16, v82
	v_fma_f32 v91, -v91, v164, v107
	v_pk_add_f32 v[128:129], v[128:129], v[190:191]
	v_and_b32_e32 v191, 0xffff0000, v78
	v_lshlrev_b32_e32 v190, 16, v78
	v_div_fmas_f32 v91, v91, v106, v164
	v_and_b32_e32 v165, 0xffff0000, v102
	v_lshlrev_b32_e32 v164, 16, v102
	v_pk_add_f32 v[128:129], v[128:129], v[190:191]
	v_and_b32_e32 v191, 0xffff0000, v98
	v_lshlrev_b32_e32 v190, 16, v98
	v_pk_add_f32 v[128:129], v[128:129], v[164:165]
	v_and_b32_e32 v215, 0xffff0000, v114
	v_lshlrev_b32_e32 v214, 16, v114
	v_pk_add_f32 v[128:129], v[128:129], v[190:191]
	v_and_b32_e32 v219, 0xffff0000, v110
	v_lshlrev_b32_e32 v218, 16, v110
	v_pk_add_f32 v[128:129], v[128:129], v[214:215]
	v_lshlrev_b32_e32 v74, 16, v71
	v_pk_add_f32 v[128:129], v[128:129], v[218:219]
	v_lshlrev_b32_e32 v70, 16, v83
	v_pk_add_f32 v[108:109], v[128:129], v[108:109]
	v_and_b32_e32 v129, 0xffff0000, v154
	v_pk_add_f32 v[108:109], v[108:109], v[168:169]
	v_lshlrev_b32_e32 v128, 16, v154
	v_pk_add_f32 v[108:109], v[108:109], v[128:129]
	v_and_b32_e32 v129, 0xffff0000, v150
	v_lshlrev_b32_e32 v128, 16, v150
	v_pk_add_f32 v[108:109], v[108:109], v[128:129]
	v_and_b32_e32 v129, 0xffff0000, v103
	v_lshlrev_b32_e32 v128, 16, v103
	v_pk_add_f32 v[102:103], v[130:131], v[192:193]
	v_and_b32_e32 v131, 0xffff0000, v67
	v_pk_add_f32 v[102:103], v[102:103], v[220:221]
	v_lshlrev_b32_e32 v130, 16, v67
	v_pk_add_f32 v[66:67], v[102:103], v[130:131]
	v_and_b32_e32 v103, 0xffff0000, v75
	v_lshlrev_b32_e32 v102, 16, v75
	v_pk_add_f32 v[66:67], v[66:67], v[102:103]
	v_and_b32_e32 v75, 0xffff0000, v71
	v_pk_add_f32 v[66:67], v[66:67], v[74:75]
	v_and_b32_e32 v71, 0xffff0000, v83
	v_pk_add_f32 v[66:67], v[66:67], v[70:71]
	v_and_b32_e32 v71, 0xffff0000, v79
	v_lshlrev_b32_e32 v70, 16, v79
	v_pk_add_f32 v[66:67], v[66:67], v[70:71]
	v_and_b32_e32 v71, 0xffff0000, v99
	v_lshlrev_b32_e32 v70, 16, v99
; DEVI float bfs(short h) { return __uint_as_float(((unsigned)(u16)h) << 16); }
; DEVI float silu_f(float x) { return x / (1.f + __expf(-x)); }
; __device__ void phase_p2(const P& p, int l) {
;     ...
;       float ic = 1.f / (float)(hi - lo + 1);
; #pragma unroll
;       for (int i = 0; i < 8; ++i) s[i] = s[i] * ic - bfs(wv[8][i]);
;       st8((u16*)(ws + O_DPOOL) + (size_t)r * 512 + lane * 8, s);
;     }
; #pragma unroll
;     for (int part = 0; part < 2; ++part) {
;       float a[8] = {0, 0, 0, 0, 0, 0, 0, 0};
; #pragma unroll
;       for (int j = 0; j < 4; ++j)
; #pragma unroll
;         for (int i = 0; i < 8; ++i) a[i] += bfs(cv[part][j][i]) * cw[part][j][i];
;       const float ksc = part ? 0.08838834764831845f : 1.f;
; #pragma unroll
;       for (int i = 0; i < 8; ++i) a[i] = silu_f(a[i]) * ksc;
	v_pk_add_f32 v[66:67], v[66:67], v[128:129]
	v_and_b32_e32 v75, 0xffff0000, v115
	v_lshlrev_b32_e32 v74, 16, v115
	v_pk_add_f32 v[66:67], v[66:67], v[70:71]
	v_and_b32_e32 v79, 0xffff0000, v111
	v_lshlrev_b32_e32 v78, 16, v111
	v_pk_add_f32 v[66:67], v[66:67], v[74:75]
	v_pk_add_f32 v[74:75], v[132:133], v[216:217]
	v_pk_add_f32 v[66:67], v[66:67], v[78:79]
	v_pk_add_f32 v[74:75], v[74:75], v[222:223]
	v_and_b32_e32 v79, 0xffff0000, v68
	v_lshlrev_b32_e32 v78, 16, v68
	v_pk_add_f32 v[74:75], v[74:75], v[78:79]
	v_and_b32_e32 v79, 0xffff0000, v76
	v_lshlrev_b32_e32 v78, 16, v76
	v_pk_add_f32 v[66:67], v[66:67], v[226:227]
	v_pk_add_f32 v[74:75], v[74:75], v[78:79]
	v_and_b32_e32 v79, 0xffff0000, v72
	v_lshlrev_b32_e32 v78, 16, v72
	v_pk_add_f32 v[66:67], v[66:67], v[228:229]
	v_and_b32_e32 v71, 0xffff0000, v155
	v_lshlrev_b32_e32 v70, 16, v155
	v_pk_add_f32 v[74:75], v[74:75], v[78:79]
	v_and_b32_e32 v79, 0xffff0000, v84
	v_lshlrev_b32_e32 v78, 16, v84
	v_pk_add_f32 v[66:67], v[66:67], v[70:71]
	v_and_b32_e32 v71, 0xffff0000, v151
	v_lshlrev_b32_e32 v70, 16, v151
	v_pk_add_f32 v[74:75], v[74:75], v[78:79]
	v_and_b32_e32 v79, 0xffff0000, v80
	v_lshlrev_b32_e32 v78, 16, v80
	v_pk_add_f32 v[66:67], v[66:67], v[70:71]
	v_and_b32_e32 v71, 0xffff0000, v104
	v_lshlrev_b32_e32 v70, 16, v104
	v_pk_add_f32 v[74:75], v[74:75], v[78:79]
	v_and_b32_e32 v79, 0xffff0000, v100
	v_lshlrev_b32_e32 v78, 16, v100
	v_pk_add_f32 v[74:75], v[74:75], v[70:71]
	v_and_b32_e32 v83, 0xffff0000, v116
	v_lshlrev_b32_e32 v82, 16, v116
	v_pk_add_f32 v[74:75], v[74:75], v[78:79]
	v_and_b32_e32 v99, 0xffff0000, v112
	v_lshlrev_b32_e32 v98, 16, v112
	v_pk_add_f32 v[74:75], v[74:75], v[82:83]
	v_and_b32_e32 v79, 0xffff0000, v156
	v_pk_add_f32 v[74:75], v[74:75], v[98:99]
	v_lshlrev_b32_e32 v78, 16, v156
	v_pk_add_f32 v[74:75], v[74:75], v[166:167]
	v_pk_add_f32 v[94:95], v[94:95], 0 op_sel_hi:[1,0]
	v_pk_add_f32 v[74:75], v[74:75], v[162:163]
	v_and_b32_e32 v83, 0xffff0000, v69
	v_pk_add_f32 v[74:75], v[74:75], v[78:79]
	v_and_b32_e32 v79, 0xffff0000, v152
	v_lshlrev_b32_e32 v78, 16, v152
	v_pk_add_f32 v[74:75], v[74:75], v[78:79]
	v_pk_add_f32 v[78:79], v[94:95], v[126:127]
	v_lshlrev_b32_e32 v82, 16, v69
	v_pk_add_f32 v[78:79], v[78:79], v[224:225]
	v_lshlrev_b32_e32 v76, 16, v73
	v_pk_add_f32 v[68:69], v[78:79], v[82:83]
	v_and_b32_e32 v79, 0xffff0000, v77
	v_lshlrev_b32_e32 v78, 16, v77
	v_pk_add_f32 v[68:69], v[68:69], v[78:79]
	v_and_b32_e32 v77, 0xffff0000, v73
	v_pk_add_f32 v[68:69], v[68:69], v[76:77]
	v_and_b32_e32 v73, 0xffff0000, v85
	v_lshlrev_b32_e32 v72, 16, v85
	v_div_fixup_f32 v106, v91, v90, 1.0
	v_pk_add_f32 v[68:69], v[68:69], v[72:73]
	v_and_b32_e32 v73, 0xffff0000, v81
	v_lshlrev_b32_e32 v72, 16, v81
	v_pk_fma_f32 v[70:71], v[106:107], v[74:75], v[70:71] op_sel_hi:[0,1,1] neg_lo:[0,0,1] neg_hi:[0,0,1]
	v_and_b32_e32 v75, 0xffff0000, v105
	v_lshlrev_b32_e32 v74, 16, v105
	v_pk_add_f32 v[68:69], v[68:69], v[72:73]
	v_and_b32_e32 v73, 0xffff0000, v101
	v_lshlrev_b32_e32 v72, 16, v101
	v_pk_add_f32 v[68:69], v[68:69], v[74:75]
	v_and_b32_e32 v77, 0xffff0000, v117
	v_lshlrev_b32_e32 v76, 16, v117
	v_pk_add_f32 v[68:69], v[68:69], v[72:73]
	v_and_b32_e32 v79, 0xffff0000, v113
	v_lshlrev_b32_e32 v78, 16, v113
	v_pk_add_f32 v[68:69], v[68:69], v[76:77]
	v_and_b32_e32 v73, 0xffff0000, v157
	v_pk_add_f32 v[68:69], v[68:69], v[78:79]
	v_lshlrev_b32_e32 v72, 16, v157
	v_pk_add_f32 v[68:69], v[68:69], v[92:93]
	v_pk_fma_f32 v[108:109], v[106:107], v[108:109], v[164:165] op_sel_hi:[0,1,1] neg_lo:[0,0,1] neg_hi:[0,0,1]
	v_pk_add_f32 v[68:69], v[68:69], v[96:97]
	v_pk_fma_f32 v[66:67], v[106:107], v[66:67], v[128:129] op_sel_hi:[0,1,1] neg_lo:[0,0,1] neg_hi:[0,0,1]
	v_pk_add_f32 v[68:69], v[68:69], v[72:73]
	v_and_b32_e32 v73, 0xffff0000, v153
	v_lshlrev_b32_e32 v72, 16, v153
	v_pk_add_f32 v[68:69], v[68:69], v[72:73]
	v_bfe_u32 v76, v67, 16, 1
	v_pk_fma_f32 v[68:69], v[106:107], v[68:69], v[74:75] op_sel_hi:[0,1,1] neg_lo:[0,0,1] neg_hi:[0,0,1]
	v_bfe_u32 v72, v69, 16, 1
	v_bfe_u32 v73, v68, 16, 1
	v_bfe_u32 v74, v71, 16, 1
	v_bfe_u32 v75, v70, 16, 1
	v_bfe_u32 v77, v66, 16, 1
	v_bfe_u32 v78, v109, 16, 1
	v_bfe_u32 v79, v108, 16, 1
	v_add3_u32 v79, v108, v79, s33
	v_add3_u32 v78, v109, v78, s33
	v_add3_u32 v66, v66, v77, s33
	v_add3_u32 v67, v67, v76, s33
	v_add3_u32 v70, v70, v75, s33
	v_add3_u32 v71, v71, v74, s33
	v_add3_u32 v68, v68, v73, s33
	v_add3_u32 v69, v69, v72, s33
	v_lshl_add_u64 v[90:91], v[180:181], 0, s[28:29]
	v_perm_b32 v69, v69, v68, s27
	v_perm_b32 v68, v71, v70, s27
	v_perm_b32 v67, v67, v66, s27
	v_perm_b32 v66, v78, v79, s27
	global_store_dwordx4 v[90:91], v[66:69], off
	v_and_b32_e32 v77, 0xffff0000, v146
	v_lshlrev_b32_e32 v76, 16, v146
	v_and_b32_e32 v69, 0xffff0000, v158
	v_lshlrev_b32_e32 v68, 16, v158
	v_pk_fma_f32 v[68:69], v[58:59], v[68:69], 0 op_sel_hi:[1,1,0]
	v_and_b32_e32 v71, 0xffff0000, v159
	v_pk_fma_f32 v[68:69], v[10:11], v[76:77], v[68:69]
	v_and_b32_e32 v77, 0xffff0000, v142
	v_lshlrev_b32_e32 v76, 16, v142
	v_pk_fma_f32 v[68:69], v[34:35], v[76:77], v[68:69]
	v_and_b32_e32 v77, 0xffff0000, v134
	v_lshlrev_b32_e32 v76, 16, v134
	v_pk_fma_f32 v[68:69], v[50:51], v[76:77], v[68:69]
	v_lshlrev_b32_e32 v70, 16, v159
	v_mul_f32_e32 v76, 0xbfb8aa3b, v68
	v_mul_f32_e32 v77, 0xbfb8aa3b, v69
	v_exp_f32_e32 v76, v76
	v_exp_f32_e32 v77, v77
	v_and_b32_e32 v79, 0xffff0000, v147
	v_lshlrev_b32_e32 v78, 16, v147
	v_pk_fma_f32 v[70:71], v[60:61], v[70:71], 0 op_sel_hi:[1,1,0]
	v_pk_add_f32 v[76:77], v[76:77], 1.0 op_sel_hi:[1,0]
	v_pk_fma_f32 v[70:71], v[12:13], v[78:79], v[70:71]
	v_rcp_f32_e32 v84, v76
	s_nop 0
	v_and_b32_e32 v79, 0xffff0000, v143
; DEVI float bfs(short h) { return __uint_as_float(((unsigned)(u16)h) << 16); }
; DEVI float silu_f(float x) { return x / (1.f + __expf(-x)); }
; __device__ void phase_p2(const P& p, int l) {
;     ...
; #pragma unroll
;     for (int part = 0; part < 2; ++part) {
;       float a[8] = {0, 0, 0, 0, 0, 0, 0, 0};
; #pragma unroll
;       for (int j = 0; j < 4; ++j)
; #pragma unroll
;         for (int i = 0; i < 8; ++i) a[i] += bfs(cv[part][j][i]) * cw[part][j][i];
;       const float ksc = part ? 0.08838834764831845f : 1.f;
; #pragma unroll
;       for (int i = 0; i < 8; ++i) a[i] = silu_f(a[i]) * ksc;
;       st8((u16*)(ws + O_QKC) + (size_t)r * 1024 + part * 512 + lane * 8, a);
	v_lshlrev_b32_e32 v78, 16, v143
	v_pk_fma_f32 v[70:71], v[36:37], v[78:79], v[70:71]
	v_fma_f32 v90, -v76, v84, 1.0
	v_fma_f32 v84, v90, v84, v84
	v_rcp_f32_e32 v90, v77
	s_nop 0
	v_and_b32_e32 v79, 0xffff0000, v135
	v_lshlrev_b32_e32 v78, 16, v135
	v_pk_fma_f32 v[70:71], v[52:53], v[78:79], v[70:71]
	v_mul_f32_e32 v78, 0xbfb8aa3b, v70
	v_mul_f32_e32 v79, 0xbfb8aa3b, v71
	v_exp_f32_e32 v78, v78
	v_exp_f32_e32 v79, v79
	v_mul_f32_e32 v76, v68, v84
	v_fma_f32 v68, -v77, v90, 1.0
	v_fma_f32 v90, v68, v90, v90
	v_pk_add_f32 v[78:79], v[78:79], 1.0 op_sel_hi:[1,0]
	v_rcp_f32_e32 v85, v78
	v_mov_b32_e32 v68, v90
	s_nop 0
	v_mul_f32_e32 v77, v69, v68
	v_and_b32_e32 v73, 0xffff0000, v160
	v_fma_f32 v68, -v78, v85, 1.0
	v_fma_f32 v85, v68, v85, v85
	v_rcp_f32_e32 v84, v79
	v_mov_b32_e32 v68, v85
	s_nop 0
	v_lshlrev_b32_e32 v72, 16, v160
	v_mul_f32_e32 v78, v70, v68
	v_fma_f32 v68, -v79, v84, 1.0
	v_and_b32_e32 v81, 0xffff0000, v148
	v_lshlrev_b32_e32 v80, 16, v148
	v_fma_f32 v84, v68, v84, v84
	v_pk_fma_f32 v[68:69], v[18:19], v[72:73], 0 op_sel_hi:[1,1,0]
	v_and_b32_e32 v73, 0xffff0000, v144
	v_pk_fma_f32 v[68:69], v[26:27], v[80:81], v[68:69]
	v_lshlrev_b32_e32 v72, 16, v144
	v_pk_fma_f32 v[68:69], v[2:3], v[72:73], v[68:69]
	v_and_b32_e32 v73, 0xffff0000, v136
	v_lshlrev_b32_e32 v72, 16, v136
	v_pk_fma_f32 v[68:69], v[6:7], v[72:73], v[68:69]
	v_mul_f32_e32 v72, 0xbfb8aa3b, v68
	v_mul_f32_e32 v73, 0xbfb8aa3b, v69
	v_exp_f32_e32 v72, v72
	v_exp_f32_e32 v73, v73
	s_nop 0
	v_pk_add_f32 v[72:73], v[72:73], 1.0 op_sel_hi:[1,0]
	v_mov_b32_e32 v70, v84
	v_rcp_f32_e32 v80, v72
	s_nop 0
	v_mul_f32_e32 v79, v71, v70
	v_and_b32_e32 v75, 0xffff0000, v161
	v_fma_f32 v70, -v72, v80, 1.0
	v_fma_f32 v80, v70, v80, v80
	v_mov_b32_e32 v70, v80
	v_rcp_f32_e32 v80, v73
	s_nop 0
	v_lshlrev_b32_e32 v74, 16, v161
	v_mul_f32_e32 v68, v68, v70
	v_fma_f32 v70, -v73, v80, 1.0
	v_and_b32_e32 v83, 0xffff0000, v149
	v_lshlrev_b32_e32 v82, 16, v149
	v_fma_f32 v80, v70, v80, v80
	v_pk_fma_f32 v[70:71], v[20:21], v[74:75], 0 op_sel_hi:[1,1,0]
	v_and_b32_e32 v75, 0xffff0000, v145
	v_pk_fma_f32 v[70:71], v[28:29], v[82:83], v[70:71]
	v_lshlrev_b32_e32 v74, 16, v145
	v_pk_fma_f32 v[70:71], v[4:5], v[74:75], v[70:71]
	v_and_b32_e32 v75, 0xffff0000, v137
	v_lshlrev_b32_e32 v74, 16, v137
	v_pk_fma_f32 v[70:71], v[8:9], v[74:75], v[70:71]
	v_mul_f32_e32 v74, 0xbfb8aa3b, v70
	v_mul_f32_e32 v75, 0xbfb8aa3b, v71
	v_exp_f32_e32 v74, v74
	v_exp_f32_e32 v75, v75
	s_nop 0
	v_pk_add_f32 v[74:75], v[74:75], 1.0 op_sel_hi:[1,0]
	v_mov_b32_e32 v72, v80
	v_rcp_f32_e32 v80, v74
	s_nop 0
	v_mul_f32_e32 v69, v69, v72
	v_lshl_add_u64 v[66:67], v[178:179], 0, s[28:29]
	v_fma_f32 v72, -v74, v80, 1.0
	v_fma_f32 v80, v72, v80, v80
	v_mov_b32_e32 v72, v80
	v_rcp_f32_e32 v80, v75
	s_nop 0
	v_mul_f32_e32 v70, v70, v72
	v_bfe_u32 v82, v77, 16, 1
	v_fma_f32 v72, -v75, v80, 1.0
	v_fma_f32 v80, v72, v80, v80
	v_mov_b32_e32 v72, v80
	v_mul_f32_e32 v71, v71, v72
	v_bfe_u32 v72, v71, 16, 1
	v_bfe_u32 v73, v70, 16, 1
	v_bfe_u32 v74, v69, 16, 1
	v_bfe_u32 v75, v68, 16, 1
	v_bfe_u32 v80, v79, 16, 1
	v_bfe_u32 v81, v78, 16, 1
	v_bfe_u32 v83, v76, 16, 1
	s_mov_b32 s0, 0x1ff0a000
	v_add3_u32 v76, v76, v83, s33
	v_add3_u32 v77, v77, v82, s33
	v_add3_u32 v78, v78, v81, s33
	v_add3_u32 v79, v79, v80, s33
	v_add3_u32 v68, v68, v75, s33
	v_add3_u32 v69, v69, v74, s33
	v_add3_u32 v70, v70, v73, s33
	v_add3_u32 v71, v71, v72, s33
	v_add_co_u32_e32 v66, vcc, s0, v66
	v_perm_b32 v71, v71, v70, s27
	v_perm_b32 v70, v69, v68, s27
	v_perm_b32 v69, v79, v78, s27
	v_perm_b32 v68, v77, v76, s27
	v_addc_co_u32_e32 v67, vcc, 0, v67, vcc
	global_store_dwordx4 v[66:67], v[68:71], off
	v_and_b32_e32 v77, 0xffff0000, v118
	v_lshlrev_b32_e32 v76, 16, v118
	v_and_b32_e32 v69, 0xffff0000, v122
	v_lshlrev_b32_e32 v68, 16, v122
	v_pk_fma_f32 v[68:69], v[22:23], v[68:69], 0 op_sel_hi:[1,1,0]
	v_and_b32_e32 v85, 0xffff0000, v138
	v_lshlrev_b32_e32 v84, 16, v138
	v_pk_fma_f32 v[68:69], v[30:31], v[76:77], v[68:69]
	v_and_b32_e32 v77, 0xffff0000, v86
	v_pk_fma_f32 v[68:69], v[38:39], v[84:85], v[68:69]
	v_lshlrev_b32_e32 v76, 16, v86
	v_pk_fma_f32 v[68:69], v[54:55], v[76:77], v[68:69]
	v_and_b32_e32 v71, 0xffff0000, v123
	v_mul_f32_e32 v76, 0xbfb8aa3b, v68
	v_mul_f32_e32 v77, 0xbfb8aa3b, v69
	v_exp_f32_e32 v76, v76
	v_exp_f32_e32 v77, v77
	v_lshlrev_b32_e32 v70, 16, v123
	v_and_b32_e32 v79, 0xffff0000, v119
	v_lshlrev_b32_e32 v78, 16, v119
	v_pk_add_f32 v[76:77], v[76:77], 1.0 op_sel_hi:[1,0]
	v_pk_fma_f32 v[70:71], v[24:25], v[70:71], 0 op_sel_hi:[1,1,0]
	v_rcp_f32_e32 v86, v77
	s_nop 0
	v_and_b32_e32 v85, 0xffff0000, v139
	v_lshlrev_b32_e32 v84, 16, v139
; DEVI float bf2f(u16 h) { return __uint_as_float(((unsigned)h) << 16); }
; DEVI float bfs(short h) { return __uint_as_float(((unsigned)(u16)h) << 16); }
; DEVI float silu_f(float x) { return x / (1.f + __expf(-x)); }
; __device__ void phase_p2(const P& p, int l) {
;     ...
; #pragma unroll
;     for (int part = 0; part < 2; ++part) {
;       float a[8] = {0, 0, 0, 0, 0, 0, 0, 0};
; #pragma unroll
;       for (int j = 0; j < 4; ++j)
; #pragma unroll
;         for (int i = 0; i < 8; ++i) a[i] += bfs(cv[part][j][i]) * cw[part][j][i];
;       const float ksc = part ? 0.08838834764831845f : 1.f;
; #pragma unroll
;       for (int i = 0; i < 8; ++i) a[i] = silu_f(a[i]) * ksc;
;       st8((u16*)(ws + O_QKC) + (size_t)r * 1024 + part * 512 + lane * 8, a);
;     }
;     if (lane < 16) {
;       float gg = bf2f(dif) + bif;
;       if (lane & 4) gg = fminf(gg, 0.f) - __logf(1.f + __expf(-fabsf(gg)));
;       ((float*)(ws + O_GL))[(size_t)r * 16 + lane] = gg;
	v_pk_fma_f32 v[70:71], v[32:33], v[78:79], v[70:71]
	v_fma_f32 v95, -v77, v86, 1.0
	v_fma_f32 v86, v95, v86, v86
	v_rcp_f32_e32 v95, v76
	s_nop 0
	v_pk_fma_f32 v[70:71], v[40:41], v[84:85], v[70:71]
	v_and_b32_e32 v79, 0xffff0000, v87
	v_lshlrev_b32_e32 v78, 16, v87
	v_pk_fma_f32 v[70:71], v[56:57], v[78:79], v[70:71]
	v_mul_f32_e32 v78, 0xbfb8aa3b, v70
	v_mul_f32_e32 v79, 0xbfb8aa3b, v71
	v_exp_f32_e32 v78, v78
	v_exp_f32_e32 v79, v79
	v_mul_f32_e32 v69, v69, v86
	v_fma_f32 v77, -v76, v95, 1.0
	v_fma_f32 v95, v77, v95, v95
	v_pk_add_f32 v[78:79], v[78:79], 1.0 op_sel_hi:[1,0]
	v_rcp_f32_e32 v84, v79
	s_nop 0
	v_mov_b32_e32 v77, v95
	v_mul_f32_e32 v68, v68, v77
	v_fma_f32 v76, -v79, v84, 1.0
	v_fma_f32 v84, v76, v84, v84
	v_mov_b32_e32 v76, v84
	v_rcp_f32_e32 v84, v78
	s_nop 0
	v_and_b32_e32 v73, 0xffff0000, v124
	v_lshlrev_b32_e32 v72, 16, v124
	v_and_b32_e32 v81, 0xffff0000, v120
	v_lshlrev_b32_e32 v80, 16, v120
	v_pk_fma_f32 v[72:73], v[14:15], v[72:73], 0 op_sel_hi:[1,1,0]
	v_and_b32_e32 v91, 0xffff0000, v140
	v_lshlrev_b32_e32 v90, 16, v140
	v_mul_f32_e32 v71, v71, v76
	v_fma_f32 v76, -v78, v84, 1.0
	v_pk_fma_f32 v[72:73], v[42:43], v[80:81], v[72:73]
	v_fma_f32 v84, v76, v84, v84
	v_pk_fma_f32 v[72:73], v[46:47], v[90:91], v[72:73]
	v_and_b32_e32 v77, 0xffff0000, v88
	v_lshlrev_b32_e32 v76, 16, v88
	v_pk_fma_f32 v[72:73], v[62:63], v[76:77], v[72:73]
	v_mul_f32_e32 v76, 0xbfb8aa3b, v72
	v_mul_f32_e32 v77, 0xbfb8aa3b, v73
	v_exp_f32_e32 v76, v76
	v_exp_f32_e32 v77, v77
	s_nop 0
	v_pk_add_f32 v[76:77], v[76:77], 1.0 op_sel_hi:[1,0]
	v_mov_b32_e32 v79, v84
	v_rcp_f32_e32 v80, v77
	s_nop 0
	v_mul_f32_e32 v70, v70, v79
	v_and_b32_e32 v75, 0xffff0000, v125
	v_fma_f32 v78, -v77, v80, 1.0
	v_fma_f32 v80, v78, v80, v80
	v_lshlrev_b32_e32 v74, 16, v125
	v_and_b32_e32 v83, 0xffff0000, v121
	v_lshlrev_b32_e32 v82, 16, v121
	v_mov_b32_e32 v78, v80
	v_rcp_f32_e32 v80, v76
	v_pk_fma_f32 v[74:75], v[16:17], v[74:75], 0 op_sel_hi:[1,1,0]
	v_and_b32_e32 v93, 0xffff0000, v141
	v_lshlrev_b32_e32 v92, 16, v141
	s_nop 0
	v_pk_fma_f32 v[74:75], v[44:45], v[82:83], v[74:75]
	v_mul_f32_e32 v73, v73, v78
	v_pk_fma_f32 v[74:75], v[48:49], v[92:93], v[74:75]
	v_and_b32_e32 v79, 0xffff0000, v89
	v_lshlrev_b32_e32 v78, 16, v89
	v_pk_fma_f32 v[74:75], v[64:65], v[78:79], v[74:75]
	v_fma_f32 v77, -v76, v80, 1.0
	v_mul_f32_e32 v78, 0xbfb8aa3b, v74
	v_mul_f32_e32 v79, 0xbfb8aa3b, v75
	v_exp_f32_e32 v78, v78
	v_exp_f32_e32 v79, v79
	v_fma_f32 v80, v77, v80, v80
	v_pk_add_f32 v[78:79], v[78:79], 1.0 op_sel_hi:[1,0]
	v_mov_b32_e32 v77, v80
	v_rcp_f32_e32 v80, v79
	s_nop 0
	v_mul_f32_e32 v72, v72, v77
	v_pk_mul_f32 v[68:69], v[68:69], s[6:7] op_sel_hi:[1,0]
	v_fma_f32 v76, -v79, v80, 1.0
	v_fma_f32 v80, v76, v80, v80
	v_mov_b32_e32 v76, v80
	v_rcp_f32_e32 v80, v78
	s_nop 0
	v_mul_f32_e32 v75, v75, v76
	v_pk_mul_f32 v[70:71], v[70:71], s[6:7] op_sel_hi:[1,0]
	v_fma_f32 v76, -v78, v80, 1.0
	v_fma_f32 v80, v76, v80, v80
	v_mov_b32_e32 v76, v80
	v_mul_f32_e32 v74, v74, v76
	v_pk_mul_f32 v[72:73], v[72:73], s[6:7] op_sel_hi:[1,0]
	v_pk_mul_f32 v[74:75], v[74:75], s[6:7] op_sel_hi:[1,0]
	v_bfe_u32 v78, v73, 16, 1
	v_bfe_u32 v76, v75, 16, 1
	v_bfe_u32 v77, v74, 16, 1
	v_bfe_u32 v79, v72, 16, 1
	v_bfe_u32 v80, v71, 16, 1
	v_bfe_u32 v81, v70, 16, 1
	v_bfe_u32 v82, v69, 16, 1
	v_bfe_u32 v83, v68, 16, 1
	v_add3_u32 v68, v68, v83, s33
	v_add3_u32 v82, v69, v82, s33
	v_add3_u32 v69, v70, v81, s33
	v_add3_u32 v80, v71, v80, s33
	v_add3_u32 v70, v72, v79, s33
	v_add3_u32 v72, v73, v78, s33
	v_add3_u32 v71, v74, v77, s33
	v_add3_u32 v73, v75, v76, s33
	v_perm_b32 v71, v73, v71, s27
	v_perm_b32 v70, v72, v70, s27
	v_perm_b32 v69, v80, v69, s27
	v_perm_b32 v68, v82, v68, s27
	global_store_dwordx4 v[66:67], v[68:71], off offset:1024
	s_and_saveexec_b64 s[2:3], s[38:39]
	s_cbranch_execz .LBB0_88
	v_lshlrev_b32_e32 v66, 16, v173
	v_add_f32_e32 v66, v204, v66
	s_and_saveexec_b64 s[48:49], s[46:47]
	s_cbranch_execz .LBB0_87
	s_mov_b32 s0, 0xbfb8aa3b
	v_mul_f32_e64 v67, |v66|, s0
	v_exp_f32_e32 v67, v67
	s_mov_b32 s0, 0x800000
	v_max_f32_e32 v66, v66, v66
	v_min_f32_e32 v66, 0, v66
	v_add_f32_e32 v67, 1.0, v67
	v_cmp_gt_f32_e32 vcc, s0, v67
	s_mov_b32 s0, 0x3f317217
	s_nop 0
	v_cndmask_b32_e64 v68, 0, 32, vcc
	v_ldexp_f32 v67, v67, v68
	v_log_f32_e32 v67, v67
	s_nop 0
	v_mul_f32_e32 v68, 0x3f317217, v67
	v_fma_f32 v68, v67, s0, -v68
	v_fmac_f32_e32 v68, 0x3377d1cf, v67
	s_mov_b32 s0, 0x7f800000
	v_fmac_f32_e32 v68, 0x3f317217, v67
	v_cmp_lt_f32_e64 s[0:1], |v67|, s0
	s_nop 1
	v_cndmask_b32_e64 v67, v67, v68, s[0:1]
	v_cndmask_b32_e32 v68, 0, v199, vcc
	v_sub_f32_e32 v67, v67, v68
	v_sub_f32_e32 v66, v66, v67
	s_branch .LBB0_87

; #define WAIT_V(n) asm volatile("s_waitcnt vmcnt(" #n ")" ::: "memory")
; #define BAR __builtin_amdgcn_s_barrier()
; DEVI void gemm256(const P& p, const u16* A, int lda, const u16* Bt, int ldb, int K, int brow, int bcol, int mode,
;                         int aux, int layer, int bmode) {
;     ...
;   f32x4 acc[2][2][4][2] = {};
;   bf16x8 At[4][2], B0[2][2], B1[2][2];
;     ...
;   STAGEB(SB(0, 0), bcol, 0);
;   STAGEA(SA(0, 0), brow, 0);
;   STAGEB(SB(0, 1), bcol + bhalf, 0);
;   STAGEA(SA(0, 1), brow + HALF, 0);
;   if (wr == 1) BAR;
;   WAIT_V(4);
.LBB0_189:
	s_lshl_b32 s70, s4, 8
	s_mul_i32 s97, s7, s6
	s_and_b64 s[2:3], s[46:47], exec
	s_movk_i32 s2, 0x80
	s_mul_i32 s3, s97, s5
	s_cselect_b32 s2, s2, 0x1000
	s_lshl_b32 s6, s3, 1
	v_readlane_b32 s3, v249, 20
	s_add_i32 s2, s97, s2
	s_and_b32 s29, s29, 0xffff
	v_add_u32_e32 v145, s3, v0
	v_add_u32_e32 v146, 0x2000, v145
	v_readfirstlane_b32 s3, v145
	s_mov_b32 m0, s3
	v_readfirstlane_b32 s3, v146
	v_add_u32_e32 v147, 16, v0
	s_mul_i32 s2, s2, s5
	v_mul_lo_u32 v2, v2, s9
	buffer_load_dwordx4 v136, s[28:31], s6 offen lds
	s_mov_b32 m0, s3
	s_mul_i32 s7, s9, s70
	v_readfirstlane_b32 s3, v147
	v_add_u32_e32 v148, 0x2000, v147
	s_lshl_b32 s8, s2, 1
	v_readlane_b32 s2, v249, 21
	s_and_b32 s45, s45, 0xffff
	s_mov_b32 s46, s30
	s_mov_b32 s47, s31
	v_add_lshl_u32 v143, v3, v2, 1
	v_mul_lo_u32 v2, v4, s9
	buffer_load_dwordx4 v137, s[28:31], s6 offen lds
	s_lshl_b32 s10, s7, 1
	s_mov_b32 m0, s3
	v_readfirstlane_b32 s3, v148
	v_add_u32_e32 v150, s2, v0
	v_add_lshl_u32 v142, v5, v2, 1
	buffer_load_dwordx4 v143, s[44:47], s10 offen lds
	s_mov_b32 m0, s3
	v_readfirstlane_b32 s2, v150
	v_add_u32_e32 v151, 0x2000, v150
	buffer_load_dwordx4 v142, s[44:47], s10 offen lds
	s_mov_b32 m0, s2
	v_readfirstlane_b32 s2, v151
	buffer_load_dwordx4 v136, s[28:31], s8 offen lds
	s_mov_b32 m0, s2
	s_lshl_b32 s2, s9, 7
	v_add_u32_e32 v152, 0x4000, v147
	s_add_i32 s7, s7, s2
	v_readfirstlane_b32 s3, v152
	v_add_u32_e32 v153, 0x6000, v147
	buffer_load_dwordx4 v137, s[28:31], s8 offen lds
	s_lshl_b32 s2, s7, 1
	s_mov_b32 m0, s3
	v_readfirstlane_b32 s3, v153
	buffer_load_dwordx4 v143, s[44:47], s2 offen lds
	s_mov_b32 m0, s3
	v_ashrrev_i32_e32 v132, 8, v130
	buffer_load_dwordx4 v142, s[44:47], s2 offen lds
	v_mov_b32_e32 v62, 0
	v_mov_b32_e32 v63, 0
	v_mov_b32_e32 v64, 0
	v_mov_b32_e32 v65, 0
	v_mov_b32_e32 v82, 0
	v_mov_b32_e32 v83, 0
	v_mov_b32_e32 v84, 0
	v_mov_b32_e32 v85, 0
	v_mov_b32_e32 v98, 0
	v_mov_b32_e32 v99, 0
	v_mov_b32_e32 v100, 0
	v_mov_b32_e32 v101, 0
	v_mov_b32_e32 v110, 0
	v_mov_b32_e32 v111, 0
	v_mov_b32_e32 v112, 0
	v_mov_b32_e32 v113, 0
	v_mov_b32_e32 v114, 0
	v_mov_b32_e32 v115, 0
	v_mov_b32_e32 v116, 0
	v_mov_b32_e32 v117, 0
	v_mov_b32_e32 v118, 0
	v_mov_b32_e32 v119, 0
	v_mov_b32_e32 v120, 0
	v_mov_b32_e32 v121, 0
	v_mov_b32_e32 v122, 0
	v_mov_b32_e32 v123, 0
	v_mov_b32_e32 v124, 0
	v_mov_b32_e32 v125, 0
	v_mov_b32_e32 v126, 0
	v_mov_b32_e32 v127, 0
	v_mov_b32_e32 v128, 0
	v_mov_b32_e32 v129, 0
	v_mov_b32_e32 v34, 0
	v_mov_b32_e32 v35, 0
	v_mov_b32_e32 v36, 0
	v_mov_b32_e32 v37, 0
	v_mov_b32_e32 v38, 0
	v_mov_b32_e32 v39, 0
	v_mov_b32_e32 v40, 0
	v_mov_b32_e32 v41, 0
	v_mov_b32_e32 v42, 0
	v_mov_b32_e32 v43, 0
	v_mov_b32_e32 v44, 0
	v_mov_b32_e32 v45, 0
	v_mov_b32_e32 v46, 0
	v_mov_b32_e32 v47, 0
	v_mov_b32_e32 v48, 0
	v_mov_b32_e32 v49, 0
	v_mov_b32_e32 v50, 0
	v_mov_b32_e32 v51, 0
	v_mov_b32_e32 v52, 0
	v_mov_b32_e32 v53, 0
	v_mov_b32_e32 v54, 0
	v_mov_b32_e32 v55, 0
	v_mov_b32_e32 v56, 0
	v_mov_b32_e32 v57, 0
	v_mov_b32_e32 v58, 0
	v_mov_b32_e32 v59, 0
	v_mov_b32_e32 v60, 0
	v_mov_b32_e32 v61, 0
	v_mov_b32_e32 v70, 0
	v_mov_b32_e32 v71, 0
	v_mov_b32_e32 v72, 0
	v_mov_b32_e32 v73, 0
	v_mov_b32_e32 v66, 0
	v_mov_b32_e32 v67, 0
	v_mov_b32_e32 v68, 0
	v_mov_b32_e32 v69, 0
	v_mov_b32_e32 v74, 0
	v_mov_b32_e32 v75, 0
	v_mov_b32_e32 v76, 0
	v_mov_b32_e32 v77, 0
	v_mov_b32_e32 v78, 0
	v_mov_b32_e32 v79, 0
	v_mov_b32_e32 v80, 0
	v_mov_b32_e32 v81, 0
	v_mov_b32_e32 v86, 0
	v_mov_b32_e32 v87, 0
	v_mov_b32_e32 v88, 0
	v_mov_b32_e32 v89, 0
	v_mov_b32_e32 v90, 0
	v_mov_b32_e32 v91, 0
	v_mov_b32_e32 v92, 0
	v_mov_b32_e32 v93, 0
	v_mov_b32_e32 v94, 0
	v_mov_b32_e32 v95, 0
	v_mov_b32_e32 v96, 0
	v_mov_b32_e32 v97, 0
	v_mov_b32_e32 v102, 0
	v_mov_b32_e32 v103, 0
	v_mov_b32_e32 v104, 0
	v_mov_b32_e32 v105, 0
	v_mov_b32_e32 v106, 0
	v_mov_b32_e32 v107, 0
	v_mov_b32_e32 v108, 0
	v_mov_b32_e32 v109, 0
	v_cmp_eq_u32_e32 vcc, 1, v132
	s_and_saveexec_b64 s[2:3], vcc
	s_cbranch_execz .LBB0_191
	s_barrier
; #define WAIT_V(n) asm volatile("s_waitcnt vmcnt(" #n ")" ::: "memory")
; #define BAR __builtin_amdgcn_s_barrier()
; DEVI void gemm256(const P& p, const u16* A, int lda, const u16* Bt, int ldb, int K, int brow, int bcol, int mode,
;                         int aux, int layer, int bmode) {
;     ...
;   if (wr == 1) BAR;
;   WAIT_V(4);
;   BAR;
;   STAGEB(SB(1, 0), bcol, 1);
;   STAGEA(SA(1, 0), brow, 1);
;   STAGEB(SB(1, 1), bcol + bhalf, 1);
;   WAIT_V(6);
;   BAR;
.LBB0_191:
	s_or_b64 exec, exec, s[2:3]
	v_readlane_b32 s12, v249, 22
	s_or_b32 s3, s6, 0x80
	s_waitcnt vmcnt(4)
	s_barrier
	v_add_u32_e32 v154, s12, v0
	v_add_u32_e32 v155, 0x2000, v154
	v_readfirstlane_b32 s11, v154
	s_mov_b32 m0, s11
	v_readfirstlane_b32 s11, v155
	buffer_load_dwordx4 v136, s[28:31], s3 offen lds
	s_mov_b32 m0, s11
	v_add_u32_e32 v156, 0x8000, v147
	buffer_load_dwordx4 v137, s[28:31], s3 offen lds
	v_readfirstlane_b32 s3, v156
	v_add_u32_e32 v157, 0xa000, v147
	s_bitset1_b32 s10, 7
	s_mov_b32 s46, s30
	s_mov_b32 s47, s31
	s_mov_b32 m0, s3
	v_readfirstlane_b32 s3, v157
	v_readlane_b32 s11, v249, 23
	buffer_load_dwordx4 v143, s[44:47], s10 offen lds
	s_mov_b32 m0, s3
	v_add_u32_e32 v161, s11, v0
	buffer_load_dwordx4 v142, s[44:47], s10 offen lds
	v_readfirstlane_b32 s10, v161
	v_add_u32_e32 v162, 0x2000, v161
	s_or_b32 s3, s8, 0x80
	s_mov_b32 m0, s10
	v_readfirstlane_b32 s10, v162
	buffer_load_dwordx4 v136, s[28:31], s3 offen lds
	s_mov_b32 m0, s10
	v_and_b32_e32 v131, 15, v130
	buffer_load_dwordx4 v137, s[28:31], s3 offen lds
	v_bfe_u32 v134, v130, 4, 2
	v_lshlrev_b32_e32 v4, 2, v130
	v_lshlrev_b32_e32 v2, 4, v134
	v_lshlrev_b32_e32 v3, 6, v131
	v_and_b32_e32 v4, 32, v4
	v_bitop3_b32 v3, v2, v4, v3 bitop3:0x36
	v_readlane_b32 s3, v249, 20
	v_lshrrev_b32_e32 v133, 4, v130
	s_waitcnt vmcnt(27)
	v_lshlrev_b32_e32 v11, 6, v130
	v_add_u32_e32 v5, s3, v3
	v_readlane_b32 s3, v249, 21
	s_waitcnt vmcnt(6)
	v_and_b32_e32 v135, 12, v133
	v_lshlrev_b32_e32 v10, 13, v132
	v_add_u32_e32 v6, s3, v3
	s_movk_i32 s3, 0x3c0
	v_and_or_b32 v2, v11, s3, v2
	s_add_i32 s3, s70, 0x80
	s_lshr_b32 s2, s5, 6
	v_add_u32_e32 v7, s12, v3
	v_add_u32_e32 v8, s11, v3
	v_lshlrev_b32_e32 v9, 10, v135
	v_add_u32_e32 v3, 16, v3
	v_xad_u32 v4, v2, v4, 16
	v_or_b32_e32 v11, 0x800, v10
	v_or_b32_e32 v12, 0x1000, v10
	v_or_b32_e32 v13, 0x1800, v10
	s_mul_i32 s3, s9, s3
	s_lshl_b32 s4, s4, 9
	v_mov_b32_e32 v2, 0
	s_xor_b64 s[36:37], s[36:37], -1
	s_xor_b64 s[78:79], s[54:55], -1
	s_add_i32 s2, s2, -2
	v_add_u32_e32 v159, 0xc000, v147
	v_add_u32_e32 v158, 0xe000, v147
	s_lshl_b32 s3, s3, 1
	s_mul_i32 s9, s4, s9
	s_mov_b32 s10, 0
	v_add_u32_e32 v163, v5, v9
	v_add_u32_e32 v141, v3, v10
	v_add_u32_e32 v140, v4, v11
	v_add_u32_e32 v139, v4, v12
	v_add_u32_e32 v138, v4, v13
	v_add_u32_e32 v160, v6, v9
	v_add_u32_e32 v149, v7, v9
	v_add_u32_e32 v144, v8, v9
	s_mov_b32 s11, 0
	v_mov_b32_e32 v3, v2
	v_mov_b32_e32 v4, v2
	v_mov_b32_e32 v5, v2
	v_mov_b32_e32 v6, v2
	v_mov_b32_e32 v7, v2
	v_mov_b32_e32 v8, v2
	v_mov_b32_e32 v9, v2
	v_mov_b32_e32 v10, v2
	v_mov_b32_e32 v11, v2
	v_mov_b32_e32 v12, v2
	v_mov_b32_e32 v13, v2
	s_waitcnt vmcnt(26)
	v_mov_b32_e32 v14, v2
	v_mov_b32_e32 v15, v2
	v_mov_b32_e32 v16, v2
	v_mov_b32_e32 v17, v2
	s_waitcnt vmcnt(25)
	v_mov_b32_e32 v18, v2
	v_mov_b32_e32 v19, v2
	v_mov_b32_e32 v20, v2
	v_mov_b32_e32 v21, v2
	s_waitcnt vmcnt(24)
	v_mov_b32_e32 v22, v2
	v_mov_b32_e32 v23, v2
	v_mov_b32_e32 v24, v2
	v_mov_b32_e32 v25, v2
	s_waitcnt vmcnt(23)
	v_mov_b32_e32 v26, v2
	v_mov_b32_e32 v27, v2
	v_mov_b32_e32 v28, v2
	v_mov_b32_e32 v29, v2
	s_waitcnt vmcnt(22)
	v_mov_b32_e32 v30, v2
	v_mov_b32_e32 v31, v2
	v_mov_b32_e32 v32, v2
	v_mov_b32_e32 v33, v2
	s_waitcnt vmcnt(14)
	s_barrier
